# speedup vs baseline: 1.0075x; 1.0029x over previous
; __global__ __launch_bounds__(512, 2)
; void hybrid_megakernel(Params p_in) {
;     ...
;         for (int t = bid; t < ngt; t += G) {
;           const GemmArgs g = load_desc(dt + t);
;           __syncthreads();
;           gemm_tile(g, (bf16*)shm, tid, wid, ws, pp->g_in + (l + 1 < DEPTH ? (l + 1) * DM : 0));
.LBB0_34:
	s_add_i32 s8, s8, s52
	s_cmp_ge_i32 s8, s38
	s_cbranch_scc1 .LBB0_94
	s_waitcnt lgkmcnt(0)
	v_mov_b32_e32 v4, s84
	v_mov_b32_e32 v5, s85
	v_mov_b32_e32 v6, s86
	v_mov_b32_e32 v7, s87
	v_mov_b32_e32 v16, s88
	v_mov_b32_e32 v17, s89
	v_mov_b32_e32 v18, s90
	v_mov_b32_e32 v19, s91
	v_mov_b32_e32 v8, s92
	v_mov_b32_e32 v9, s93
	v_mov_b32_e32 v10, s94
	v_mov_b32_e32 v11, s95
	v_mov_b32_e32 v12, s96
	v_mov_b32_e32 v13, s97
	v_mov_b32_e32 v14, s98
	v_mov_b32_e32 v15, s99
	s_add_i32 s75, s26, 0x10000
	s_mov_b32 m0, s75
	s_barrier
	v_readfirstlane_b32 s10, v6
	s_branch .Ltile_join3
.LBB0_35:
	s_ashr_i32 s9, s8, 31
	s_lshl_b64 s[0:1], s[8:9], 6
	s_add_u32 s0, s57, s0
	s_addc_u32 s1, s61, s1
	global_load_dwordx4 v[4:7], v3, s[0:1]
	global_load_dwordx4 v[8:11], v3, s[0:1] offset:32
	s_add_i32 s75, s26, 0x10000
	global_load_dwordx4 v[12:15], v3, s[0:1] offset:48
	global_load_dwordx4 v[16:19], v3, s[0:1] offset:16
	s_mov_b32 m0, s75
	s_barrier
	s_waitcnt vmcnt(0)
	v_readfirstlane_b32 s10, v6
	s_waitcnt vmcnt(2)
.Ltile_join3:
	v_readfirstlane_b32 s2, v8
	v_readfirstlane_b32 s16, v9
	s_ashr_i32 s3, s2, 31
	s_ashr_i32 s17, s16, 31
	s_lshl_b64 s[6:7], s[2:3], 7
	s_lshl_b64 s[14:15], s[16:17], 7
	v_readfirstlane_b32 s11, v7
	s_add_u32 s28, s10, s14
	v_readfirstlane_b32 s0, v4
	s_addc_u32 s29, s11, s15
	s_add_i32 s77, s26, 0x12000
	v_readfirstlane_b32 s1, v5
	s_add_u32 s66, s0, s6
	s_addc_u32 s67, s1, s7
	s_add_i32 s84, s26, 0x2000
	v_mul_lo_u32 v1, s16, v145
	s_add_u32 s48, s28, s14
	s_waitcnt lgkmcnt(0)
	v_add_lshl_u32 v2, v1, v150, 1
	s_addc_u32 s49, s29, s15
	s_add_i32 s85, s26, 0x14000
	v_mul_lo_u32 v0, s2, v145
	global_load_lds_dwordx4 v2, s[10:11]
	s_mov_b32 m0, s77
	s_add_u32 s50, s48, s14
	v_add_lshl_u32 v0, v0, v150, 1
	global_load_lds_dwordx4 v2, s[28:29]
	s_mov_b32 m0, s26
	s_addc_u32 s51, s49, s15
	s_add_i32 s86, s26, 0x16000
	global_load_lds_dwordx4 v0, s[0:1]
	s_mov_b32 m0, s84
	s_add_u32 s72, s66, s6
	global_load_lds_dwordx4 v0, s[66:67]
	s_mov_b32 m0, s85
	s_addc_u32 s73, s67, s7
	s_add_i32 s87, s26, 0x4000
	global_load_lds_dwordx4 v2, s[48:49]
	s_mov_b32 m0, s86
	s_add_u32 s28, s72, s6
	global_load_lds_dwordx4 v2, s[50:51]
	s_mov_b32 m0, s87
	s_addc_u32 s29, s73, s7
	s_add_i32 s88, s26, 0x6000
	global_load_lds_dwordx4 v0, s[72:73]
	s_mov_b32 m0, s88
	s_waitcnt vmcnt(7)
	v_readfirstlane_b32 s69, v17
	global_load_lds_dwordx4 v0, s[28:29]
	v_readlane_b32 s28, v255, 7
	v_readlane_b32 s29, v255, 8
	v_readfirstlane_b32 s68, v16
	v_readfirstlane_b32 s71, v19
	v_readfirstlane_b32 s70, v18
	v_readfirstlane_b32 s66, v10
	v_readfirstlane_b32 s67, v11
	v_readfirstlane_b32 s89, v12
	v_readfirstlane_b32 s9, v13
	v_readfirstlane_b32 s74, v14
	s_andn2_b64 vcc, exec, s[28:29]
	v_readfirstlane_b32 s83, v15
	s_cbranch_vccnz .LBB0_37
	s_barrier
